# attention: LDS read waits counted per fragment (lgkmcnt(2)) instead of draining all outstanding reads before every third MFMA group
# speedup vs baseline: 1.0082x; 1.0039x over previous
.LBB0_397:
	s_and_b32 s38, s74, 0x10000
	s_add_i32 s76, s38, 0
	s_cmp_lg_u32 s72, s74
	s_cselect_b64 s[38:39], -1, 0
	v_xor_b32_e32 v116, 0x80000000, v163
	s_or_b64 s[64:65], s[62:63], s[38:39]
	v_mov_b32_e32 v117, v116
	v_mov_b32_e32 v118, v116
	v_mov_b32_e32 v119, v116
	v_add_u32_e32 v2, s76, v154
	ds_read_b128 v[84:87], v2
	v_add_u32_e32 v0, s76, v155
	ds_read_b128 v[88:91], v0
	ds_read_b128 v[92:95], v2 offset:4096
	s_waitcnt lgkmcnt(2)
	v_mfma_f32_16x16x32_bf16 v[84:87], v[84:87], v[28:31], v[116:119]
	ds_read_b128 v[96:99], v0 offset:4096
	s_waitcnt lgkmcnt(2)
	v_mfma_f32_16x16x32_bf16 v[84:87], v[88:91], v[32:35], v[84:87]
	ds_read_b128 v[88:91], v2 offset:8192
	s_waitcnt lgkmcnt(2)
	v_mfma_f32_16x16x32_bf16 v[92:95], v[92:95], v[28:31], v[116:119]
	ds_read_b128 v[100:103], v0 offset:8192
	s_waitcnt lgkmcnt(2)
	v_mfma_f32_16x16x32_bf16 v[92:95], v[96:99], v[32:35], v[92:95]
	ds_read_b128 v[104:107], v2 offset:12288
	s_waitcnt lgkmcnt(2)
	v_mfma_f32_16x16x32_bf16 v[88:91], v[88:91], v[28:31], v[116:119]
	ds_read_b128 v[108:111], v0 offset:12288
	s_waitcnt lgkmcnt(2)
	v_mfma_f32_16x16x32_bf16 v[96:99], v[100:103], v[32:35], v[88:91]
	s_waitcnt lgkmcnt(1)
	v_mfma_f32_16x16x32_bf16 v[88:91], v[104:107], v[28:31], v[116:119]
	s_waitcnt lgkmcnt(0)
	v_mfma_f32_16x16x32_bf16 v[88:91], v[108:111], v[32:35], v[88:91]
	v_mov_b32_e32 v100, 0xf149f2ca
	s_and_b64 vcc, exec, s[64:65]
	v_mov_b32_e32 v101, 0xf149f2ca
	v_mov_b32_e32 v102, 0xf149f2ca
	v_mov_b32_e32 v103, 0xf149f2ca
	v_mov_b32_e32 v104, 0xf149f2ca
	v_mov_b32_e32 v105, 0xf149f2ca
	v_mov_b32_e32 v106, 0xf149f2ca
	v_mov_b32_e32 v107, 0xf149f2ca
	v_mov_b32_e32 v108, 0xf149f2ca
	v_mov_b32_e32 v109, 0xf149f2ca
	v_mov_b32_e32 v110, 0xf149f2ca
	v_mov_b32_e32 v111, 0xf149f2ca
	v_mov_b32_e32 v112, 0xf149f2ca
	v_mov_b32_e32 v113, 0xf149f2ca
	v_mov_b32_e32 v114, 0xf149f2ca
	v_mov_b32_e32 v115, 0xf149f2ca
	s_cbranch_vccz .LBB0_399
	ds_read_b128 v[100:103], v2 offset:32768
	ds_read_b128 v[104:107], v0 offset:32768
	ds_read_b128 v[108:111], v2 offset:36864
	s_waitcnt lgkmcnt(2)
	v_mfma_f32_16x16x32_bf16 v[100:103], v[100:103], v[28:31], v[116:119]
	ds_read_b128 v[120:123], v0 offset:36864
	s_waitcnt lgkmcnt(2)
	v_mfma_f32_16x16x32_bf16 v[112:115], v[104:107], v[32:35], v[100:103]
	s_nop 4
	ds_read_b128 v[100:103], v2 offset:40960
	s_waitcnt lgkmcnt(2)
	v_mfma_f32_16x16x32_bf16 v[104:107], v[108:111], v[28:31], v[116:119]
	ds_read_b128 v[124:127], v0 offset:40960
	s_waitcnt lgkmcnt(2)
	v_mfma_f32_16x16x32_bf16 v[108:111], v[120:123], v[32:35], v[104:107]
	ds_read_b128 v[120:123], v2 offset:45056
	s_waitcnt lgkmcnt(2)
	v_mfma_f32_16x16x32_bf16 v[100:103], v[100:103], v[28:31], v[116:119]
	ds_read_b128 v[128:131], v0 offset:45056
	s_waitcnt lgkmcnt(2)
	v_mfma_f32_16x16x32_bf16 v[104:107], v[124:127], v[32:35], v[100:103]
	s_waitcnt lgkmcnt(1)
	v_mfma_f32_16x16x32_bf16 v[100:103], v[120:123], v[28:31], v[116:119]
	s_waitcnt lgkmcnt(0)
	v_mfma_f32_16x16x32_bf16 v[100:103], v[128:131], v[32:35], v[100:103]

.LBB0_404:
	v_exp_f32_e32 v0, v84
	v_exp_f32_e32 v2, v85
	v_exp_f32_e32 v3, v86
	v_exp_f32_e32 v164, v87
	v_exp_f32_e32 v165, v92
	v_exp_f32_e32 v166, v93
	v_exp_f32_e32 v167, v94
	v_exp_f32_e32 v168, v95
	v_exp_f32_e32 v169, v96
	v_exp_f32_e32 v170, v97
	v_exp_f32_e32 v171, v98
	v_exp_f32_e32 v172, v99
	v_exp_f32_e32 v173, v88
	v_exp_f32_e32 v174, v89
	v_exp_f32_e32 v175, v90
	v_exp_f32_e32 v176, v91
	v_exp_f32_e32 v177, v112
	v_exp_f32_e32 v178, v113
	v_exp_f32_e32 v179, v114
	v_exp_f32_e32 v180, v115
	v_exp_f32_e32 v181, v108
	v_exp_f32_e32 v182, v109
	v_exp_f32_e32 v183, v110
	v_exp_f32_e32 v184, v111
	v_exp_f32_e32 v185, v104
	v_exp_f32_e32 v186, v105
	v_exp_f32_e32 v187, v106
	v_exp_f32_e32 v188, v107
	v_exp_f32_e32 v189, v100
	v_exp_f32_e32 v190, v101
	v_exp_f32_e32 v191, v102
	v_exp_f32_e32 v192, v103
	v_xor_b32_e32 v132, 0x80000000, v161
	v_mov_b32_e32 v133, v132
	v_mov_b32_e32 v134, v132
	v_mov_b32_e32 v135, v132
	v_cvt_pk_bf16_f32 v92, v0, v2
	v_cvt_pk_bf16_f32 v93, v3, v164
	v_cvt_pk_bf16_f32 v94, v165, v166
	v_cvt_pk_bf16_f32 v95, v167, v168
	v_cvt_pk_bf16_f32 v96, v169, v170
	v_cvt_pk_bf16_f32 v97, v171, v172
	v_cvt_pk_bf16_f32 v98, v173, v174
	v_cvt_pk_bf16_f32 v99, v175, v176
	v_cvt_pk_bf16_f32 v84, v177, v178
	v_cvt_pk_bf16_f32 v85, v179, v180
	v_cvt_pk_bf16_f32 v86, v181, v182
	v_cvt_pk_bf16_f32 v87, v183, v184
	v_cvt_pk_bf16_f32 v88, v185, v186
	v_cvt_pk_bf16_f32 v89, v187, v188
	v_cvt_pk_bf16_f32 v90, v189, v190
	v_cvt_pk_bf16_f32 v91, v191, v192
	v_add_u32_e32 v194, s76, v156
	ds_read_b128 v[100:103], v194
	v_add_u32_e32 v193, s76, v157
	ds_read_b128 v[104:107], v193
	ds_read_b128 v[108:111], v194 offset:4096
	s_waitcnt lgkmcnt(2)
	v_mfma_f32_16x16x32_bf16 v[100:103], v[100:103], v[36:39], v[132:135]
	ds_read_b128 v[112:115], v193 offset:4096
	s_waitcnt lgkmcnt(2)
	v_mfma_f32_16x16x32_bf16 v[100:103], v[104:107], v[40:43], v[100:103]
	ds_read_b128 v[104:107], v194 offset:8192
	s_waitcnt lgkmcnt(2)
	v_mfma_f32_16x16x32_bf16 v[108:111], v[108:111], v[36:39], v[132:135]
	ds_read_b128 v[116:119], v193 offset:8192
	s_waitcnt lgkmcnt(2)
	v_mfma_f32_16x16x32_bf16 v[108:111], v[112:115], v[40:43], v[108:111]
	ds_read_b128 v[120:123], v194 offset:12288
	s_waitcnt lgkmcnt(2)
	v_mfma_f32_16x16x32_bf16 v[104:107], v[104:107], v[36:39], v[132:135]
	ds_read_b128 v[124:127], v193 offset:12288
	s_waitcnt lgkmcnt(2)
	v_mfma_f32_16x16x32_bf16 v[112:115], v[116:119], v[40:43], v[104:107]
	s_waitcnt lgkmcnt(1)
	v_mfma_f32_16x16x32_bf16 v[104:107], v[120:123], v[36:39], v[132:135]
	s_waitcnt lgkmcnt(0)
	v_mfma_f32_16x16x32_bf16 v[104:107], v[124:127], v[40:43], v[104:107]
	v_cndmask_b32_e64 v117, 0, 1, s[64:65]
	v_mov_b32_e32 v116, 0xf149f2ca
	v_cmp_ne_u32_e64 s[38:39], 1, v117
	s_andn2_b64 vcc, exec, s[64:65]
	v_mov_b32_e32 v117, 0xf149f2ca
	v_mov_b32_e32 v118, 0xf149f2ca
	v_mov_b32_e32 v119, 0xf149f2ca
	v_mov_b32_e32 v120, 0xf149f2ca
	v_mov_b32_e32 v121, 0xf149f2ca
	v_mov_b32_e32 v122, 0xf149f2ca
	v_mov_b32_e32 v123, 0xf149f2ca
	v_mov_b32_e32 v124, 0xf149f2ca
	v_mov_b32_e32 v125, 0xf149f2ca
	v_mov_b32_e32 v126, 0xf149f2ca
	v_mov_b32_e32 v127, 0xf149f2ca
	v_mov_b32_e32 v128, 0xf149f2ca
	v_mov_b32_e32 v129, 0xf149f2ca
	v_mov_b32_e32 v130, 0xf149f2ca
	v_mov_b32_e32 v131, 0xf149f2ca
	s_cbranch_vccnz .LBB0_406
	ds_read_b128 v[116:119], v194 offset:32768
	ds_read_b128 v[120:123], v193 offset:32768
	ds_read_b128 v[124:127], v194 offset:36864
	s_waitcnt lgkmcnt(2)
	v_mfma_f32_16x16x32_bf16 v[116:119], v[116:119], v[36:39], v[132:135]
	ds_read_b128 v[206:209], v193 offset:36864
	s_waitcnt lgkmcnt(2)
	v_mfma_f32_16x16x32_bf16 v[128:131], v[120:123], v[40:43], v[116:119]
	s_nop 4
	ds_read_b128 v[116:119], v194 offset:40960
	s_waitcnt lgkmcnt(2)
	v_mfma_f32_16x16x32_bf16 v[120:123], v[124:127], v[36:39], v[132:135]
	ds_read_b128 v[210:213], v193 offset:40960
	s_waitcnt lgkmcnt(2)
	v_mfma_f32_16x16x32_bf16 v[124:127], v[206:209], v[40:43], v[120:123]
	ds_read_b128 v[206:209], v194 offset:45056
	s_waitcnt lgkmcnt(2)
	v_mfma_f32_16x16x32_bf16 v[116:119], v[116:119], v[36:39], v[132:135]
	ds_read_b128 v[214:217], v193 offset:45056
	s_waitcnt lgkmcnt(2)
	v_mfma_f32_16x16x32_bf16 v[120:123], v[210:213], v[40:43], v[116:119]
	s_waitcnt lgkmcnt(1)
	v_mfma_f32_16x16x32_bf16 v[116:119], v[206:209], v[36:39], v[132:135]
	s_waitcnt lgkmcnt(0)
	v_mfma_f32_16x16x32_bf16 v[116:119], v[214:217], v[40:43], v[116:119]

.LBB0_413:
	v_add_u32_e32 v216, s76, v158
	ds_read_b128 v[218:221], v216 offset:16384
	v_add_u32_e32 v215, s76, v159
	ds_read_b128 v[232:235], v215 offset:16384
	ds_read_b128 v[236:239], v216 offset:18432
	s_waitcnt lgkmcnt(2)
	v_mfma_f32_16x16x32_bf16 v[72:75], v[218:221], v[92:95], v[72:75]
	v_mfma_f32_16x16x32_bf16 v[80:83], v[218:221], v[112:115], v[80:83]
	ds_read_b128 v[218:221], v215 offset:18432
	s_waitcnt lgkmcnt(2)
	v_mfma_f32_16x16x32_bf16 v[72:75], v[232:235], v[96:99], v[72:75]
	v_mfma_f32_16x16x32_bf16 v[80:83], v[232:235], v[108:111], v[80:83]
	ds_read_b128 v[232:235], v216 offset:20480
	s_waitcnt lgkmcnt(2)
	v_mfma_f32_16x16x32_bf16 v[68:71], v[236:239], v[92:95], v[68:71]
	v_mfma_f32_16x16x32_bf16 v[76:79], v[236:239], v[112:115], v[76:79]
	ds_read_b128 v[236:239], v215 offset:20480
	s_waitcnt lgkmcnt(2)
	v_mfma_f32_16x16x32_bf16 v[68:71], v[218:221], v[96:99], v[68:71]
	v_mfma_f32_16x16x32_bf16 v[76:79], v[218:221], v[108:111], v[76:79]
	ds_read_b128 v[218:221], v216 offset:22528
	s_waitcnt lgkmcnt(2)
	v_mfma_f32_16x16x32_bf16 v[60:63], v[232:235], v[92:95], v[60:63]
	v_mfma_f32_16x16x32_bf16 v[64:67], v[232:235], v[112:115], v[64:67]
	ds_read_b128 v[232:235], v215 offset:22528
	s_waitcnt lgkmcnt(2)
	v_mfma_f32_16x16x32_bf16 v[60:63], v[236:239], v[96:99], v[60:63]
	v_mfma_f32_16x16x32_bf16 v[64:67], v[236:239], v[108:111], v[64:67]
	ds_read_b128 v[236:239], v216 offset:24576
	s_waitcnt lgkmcnt(2)
	v_mfma_f32_16x16x32_bf16 v[48:51], v[218:221], v[92:95], v[48:51]
	v_mfma_f32_16x16x32_bf16 v[56:59], v[218:221], v[112:115], v[56:59]
	ds_read_b128 v[218:221], v215 offset:24576
	s_waitcnt lgkmcnt(2)
	v_mfma_f32_16x16x32_bf16 v[48:51], v[232:235], v[96:99], v[48:51]
	v_mfma_f32_16x16x32_bf16 v[56:59], v[232:235], v[108:111], v[56:59]
	ds_read_b128 v[232:235], v216 offset:26624
	s_waitcnt lgkmcnt(2)
	v_mfma_f32_16x16x32_bf16 v[24:27], v[236:239], v[92:95], v[24:27]
	v_mfma_f32_16x16x32_bf16 v[44:47], v[236:239], v[112:115], v[44:47]
	ds_read_b128 v[236:239], v215 offset:26624
	s_waitcnt lgkmcnt(2)
	v_mfma_f32_16x16x32_bf16 v[24:27], v[218:221], v[96:99], v[24:27]
	v_mfma_f32_16x16x32_bf16 v[44:47], v[218:221], v[108:111], v[44:47]
	ds_read_b128 v[218:221], v216 offset:28672
	s_waitcnt lgkmcnt(2)
	v_mfma_f32_16x16x32_bf16 v[16:19], v[232:235], v[92:95], v[16:19]
	v_mfma_f32_16x16x32_bf16 v[20:23], v[232:235], v[112:115], v[20:23]
	ds_read_b128 v[232:235], v215 offset:28672
	s_waitcnt lgkmcnt(2)
	v_mfma_f32_16x16x32_bf16 v[16:19], v[236:239], v[96:99], v[16:19]
	v_mfma_f32_16x16x32_bf16 v[20:23], v[236:239], v[108:111], v[20:23]
	ds_read_b128 v[236:239], v216 offset:30720
	s_waitcnt lgkmcnt(2)
	v_mfma_f32_16x16x32_bf16 v[8:11], v[218:221], v[92:95], v[8:11]
	v_mfma_f32_16x16x32_bf16 v[12:15], v[218:221], v[112:115], v[12:15]
	ds_read_b128 v[218:221], v215 offset:30720
	s_waitcnt lgkmcnt(1)
	v_mfma_f32_16x16x32_bf16 v[4:7], v[236:239], v[92:95], v[4:7]
	v_mfma_f32_16x16x32_bf16 v[52:55], v[236:239], v[112:115], v[52:55]
	v_mfma_f32_16x16x32_bf16 v[8:11], v[232:235], v[96:99], v[8:11]
	v_mfma_f32_16x16x32_bf16 v[12:15], v[232:235], v[108:111], v[12:15]
	s_waitcnt lgkmcnt(0)
	v_mfma_f32_16x16x32_bf16 v[4:7], v[218:221], v[96:99], v[4:7]
	v_mfma_f32_16x16x32_bf16 v[52:55], v[218:221], v[108:111], v[52:55]
	s_and_b64 vcc, exec, s[38:39]
	s_cbranch_vccnz .LBB0_396
	ds_read_b128 v[92:95], v216 offset:49152
	ds_read_b128 v[96:99], v215 offset:49152
	ds_read_b128 v[108:111], v216 offset:51200
	s_waitcnt lgkmcnt(2)
	v_mfma_f32_16x16x32_bf16 v[72:75], v[92:95], v[84:87], v[72:75]
	v_mfma_f32_16x16x32_bf16 v[80:83], v[92:95], v[104:107], v[80:83]
	ds_read_b128 v[92:95], v215 offset:51200
	s_waitcnt lgkmcnt(2)
	v_mfma_f32_16x16x32_bf16 v[72:75], v[96:99], v[88:91], v[72:75]
	v_mfma_f32_16x16x32_bf16 v[80:83], v[96:99], v[100:103], v[80:83]
	ds_read_b128 v[96:99], v216 offset:53248
	s_waitcnt lgkmcnt(2)
	v_mfma_f32_16x16x32_bf16 v[68:71], v[108:111], v[84:87], v[68:71]
	v_mfma_f32_16x16x32_bf16 v[76:79], v[108:111], v[104:107], v[76:79]
	ds_read_b128 v[108:111], v215 offset:53248
	s_waitcnt lgkmcnt(2)
	v_mfma_f32_16x16x32_bf16 v[68:71], v[92:95], v[88:91], v[68:71]
	v_mfma_f32_16x16x32_bf16 v[76:79], v[92:95], v[100:103], v[76:79]
	ds_read_b128 v[92:95], v216 offset:55296
	s_waitcnt lgkmcnt(2)
	v_mfma_f32_16x16x32_bf16 v[60:63], v[96:99], v[84:87], v[60:63]
	v_mfma_f32_16x16x32_bf16 v[64:67], v[96:99], v[104:107], v[64:67]
	ds_read_b128 v[96:99], v215 offset:55296
	s_waitcnt lgkmcnt(2)
	v_mfma_f32_16x16x32_bf16 v[60:63], v[108:111], v[88:91], v[60:63]
	v_mfma_f32_16x16x32_bf16 v[64:67], v[108:111], v[100:103], v[64:67]
	ds_read_b128 v[108:111], v216 offset:57344
	s_waitcnt lgkmcnt(2)
	v_mfma_f32_16x16x32_bf16 v[48:51], v[92:95], v[84:87], v[48:51]
	v_mfma_f32_16x16x32_bf16 v[56:59], v[92:95], v[104:107], v[56:59]
	ds_read_b128 v[92:95], v215 offset:57344
	s_waitcnt lgkmcnt(2)
	v_mfma_f32_16x16x32_bf16 v[48:51], v[96:99], v[88:91], v[48:51]
	v_mfma_f32_16x16x32_bf16 v[56:59], v[96:99], v[100:103], v[56:59]
	ds_read_b128 v[96:99], v216 offset:59392
	s_waitcnt lgkmcnt(2)
	v_mfma_f32_16x16x32_bf16 v[24:27], v[108:111], v[84:87], v[24:27]
	v_mfma_f32_16x16x32_bf16 v[44:47], v[108:111], v[104:107], v[44:47]
	ds_read_b128 v[108:111], v215 offset:59392
	s_waitcnt lgkmcnt(2)
	v_mfma_f32_16x16x32_bf16 v[24:27], v[92:95], v[88:91], v[24:27]
	v_mfma_f32_16x16x32_bf16 v[44:47], v[92:95], v[100:103], v[44:47]
	ds_read_b128 v[92:95], v216 offset:61440
	s_waitcnt lgkmcnt(2)
	v_mfma_f32_16x16x32_bf16 v[16:19], v[96:99], v[84:87], v[16:19]
	v_mfma_f32_16x16x32_bf16 v[20:23], v[96:99], v[104:107], v[20:23]
	ds_read_b128 v[96:99], v215 offset:61440
	s_waitcnt lgkmcnt(2)
	v_mfma_f32_16x16x32_bf16 v[16:19], v[108:111], v[88:91], v[16:19]
	v_mfma_f32_16x16x32_bf16 v[20:23], v[108:111], v[100:103], v[20:23]
	ds_read_b128 v[108:111], v216 offset:63488
	s_waitcnt lgkmcnt(2)
	v_mfma_f32_16x16x32_bf16 v[8:11], v[92:95], v[84:87], v[8:11]
	v_mfma_f32_16x16x32_bf16 v[12:15], v[92:95], v[104:107], v[12:15]
	ds_read_b128 v[92:95], v215 offset:63488
	s_waitcnt lgkmcnt(1)
	v_mfma_f32_16x16x32_bf16 v[4:7], v[108:111], v[84:87], v[4:7]
	v_mfma_f32_16x16x32_bf16 v[52:55], v[108:111], v[104:107], v[52:55]
	v_mfma_f32_16x16x32_bf16 v[8:11], v[96:99], v[88:91], v[8:11]
	v_mfma_f32_16x16x32_bf16 v[12:15], v[96:99], v[100:103], v[12:15]
	s_waitcnt lgkmcnt(0)
	v_mfma_f32_16x16x32_bf16 v[4:7], v[92:95], v[88:91], v[4:7]
	v_mfma_f32_16x16x32_bf16 v[52:55], v[92:95], v[100:103], v[52:55]
	s_branch .LBB0_396

.LBB0_421:
	s_and_b32 s38, s55, 0x10000
	s_add_i32 s65, s38, 0
	s_cmp_lg_u32 s64, s55
	s_cselect_b64 s[38:39], -1, 0
	v_xor_b32_e32 v116, 0x80000000, v163
	s_or_b64 s[46:47], s[44:45], s[38:39]
	v_mov_b32_e32 v117, v116
	v_mov_b32_e32 v118, v116
	v_mov_b32_e32 v119, v116
	v_add_u32_e32 v2, s65, v154
	ds_read_b128 v[84:87], v2
	v_add_u32_e32 v0, s65, v155
	ds_read_b128 v[88:91], v0
	ds_read_b128 v[92:95], v2 offset:4096
	s_waitcnt lgkmcnt(2)
	v_mfma_f32_16x16x32_bf16 v[84:87], v[84:87], v[36:39], v[116:119]
	ds_read_b128 v[96:99], v0 offset:4096
	s_waitcnt lgkmcnt(2)
	v_mfma_f32_16x16x32_bf16 v[84:87], v[88:91], v[40:43], v[84:87]
	ds_read_b128 v[88:91], v2 offset:8192
	s_waitcnt lgkmcnt(2)
	v_mfma_f32_16x16x32_bf16 v[92:95], v[92:95], v[36:39], v[116:119]
	ds_read_b128 v[100:103], v0 offset:8192
	s_waitcnt lgkmcnt(2)
	v_mfma_f32_16x16x32_bf16 v[92:95], v[96:99], v[40:43], v[92:95]
	ds_read_b128 v[104:107], v2 offset:12288
	s_waitcnt lgkmcnt(2)
	v_mfma_f32_16x16x32_bf16 v[88:91], v[88:91], v[36:39], v[116:119]
	ds_read_b128 v[108:111], v0 offset:12288
	s_waitcnt lgkmcnt(2)
	v_mfma_f32_16x16x32_bf16 v[96:99], v[100:103], v[40:43], v[88:91]
	s_waitcnt lgkmcnt(1)
	v_mfma_f32_16x16x32_bf16 v[88:91], v[104:107], v[36:39], v[116:119]
	s_waitcnt lgkmcnt(0)
	v_mfma_f32_16x16x32_bf16 v[88:91], v[108:111], v[40:43], v[88:91]
	v_mov_b32_e32 v100, 0xf149f2ca
	s_and_b64 vcc, exec, s[46:47]
	v_mov_b32_e32 v101, 0xf149f2ca
	v_mov_b32_e32 v102, 0xf149f2ca
	v_mov_b32_e32 v103, 0xf149f2ca
	v_mov_b32_e32 v104, 0xf149f2ca
	v_mov_b32_e32 v105, 0xf149f2ca
	v_mov_b32_e32 v106, 0xf149f2ca
	v_mov_b32_e32 v107, 0xf149f2ca
	v_mov_b32_e32 v108, 0xf149f2ca
	v_mov_b32_e32 v109, 0xf149f2ca
	v_mov_b32_e32 v110, 0xf149f2ca
	v_mov_b32_e32 v111, 0xf149f2ca
	v_mov_b32_e32 v112, 0xf149f2ca
	v_mov_b32_e32 v113, 0xf149f2ca
	v_mov_b32_e32 v114, 0xf149f2ca
	v_mov_b32_e32 v115, 0xf149f2ca
	s_cbranch_vccz .LBB0_423
	ds_read_b128 v[100:103], v2 offset:32768
	ds_read_b128 v[104:107], v0 offset:32768
	ds_read_b128 v[108:111], v2 offset:36864
	s_waitcnt lgkmcnt(2)
	v_mfma_f32_16x16x32_bf16 v[100:103], v[100:103], v[36:39], v[116:119]
	ds_read_b128 v[120:123], v0 offset:36864
	s_waitcnt lgkmcnt(2)
	v_mfma_f32_16x16x32_bf16 v[112:115], v[104:107], v[40:43], v[100:103]
	s_nop 4
	ds_read_b128 v[100:103], v2 offset:40960
	s_waitcnt lgkmcnt(2)
	v_mfma_f32_16x16x32_bf16 v[104:107], v[108:111], v[36:39], v[116:119]
	ds_read_b128 v[124:127], v0 offset:40960
	s_waitcnt lgkmcnt(2)
	v_mfma_f32_16x16x32_bf16 v[108:111], v[120:123], v[40:43], v[104:107]
	ds_read_b128 v[120:123], v2 offset:45056
	s_waitcnt lgkmcnt(2)
	v_mfma_f32_16x16x32_bf16 v[100:103], v[100:103], v[36:39], v[116:119]
	ds_read_b128 v[128:131], v0 offset:45056
	s_waitcnt lgkmcnt(2)
	v_mfma_f32_16x16x32_bf16 v[104:107], v[124:127], v[40:43], v[100:103]
	s_waitcnt lgkmcnt(1)
	v_mfma_f32_16x16x32_bf16 v[100:103], v[120:123], v[36:39], v[116:119]
	s_waitcnt lgkmcnt(0)
	v_mfma_f32_16x16x32_bf16 v[100:103], v[128:131], v[40:43], v[100:103]

.LBB0_428:
	v_exp_f32_e32 v0, v84
	v_exp_f32_e32 v2, v85
	v_exp_f32_e32 v3, v86
	v_exp_f32_e32 v164, v87
	v_exp_f32_e32 v165, v92
	v_exp_f32_e32 v166, v93
	v_exp_f32_e32 v167, v94
	v_exp_f32_e32 v168, v95
	v_exp_f32_e32 v169, v96
	v_exp_f32_e32 v170, v97
	v_exp_f32_e32 v171, v98
	v_exp_f32_e32 v172, v99
	v_exp_f32_e32 v173, v88
	v_exp_f32_e32 v174, v89
	v_exp_f32_e32 v175, v90
	v_exp_f32_e32 v176, v91
	v_exp_f32_e32 v177, v112
	v_exp_f32_e32 v178, v113
	v_exp_f32_e32 v179, v114
	v_exp_f32_e32 v180, v115
	v_exp_f32_e32 v181, v108
	v_exp_f32_e32 v182, v109
	v_exp_f32_e32 v183, v110
	v_exp_f32_e32 v184, v111
	v_exp_f32_e32 v185, v104
	v_exp_f32_e32 v186, v105
	v_exp_f32_e32 v187, v106
	v_exp_f32_e32 v188, v107
	v_exp_f32_e32 v189, v100
	v_exp_f32_e32 v190, v101
	v_exp_f32_e32 v191, v102
	v_exp_f32_e32 v192, v103
	v_xor_b32_e32 v132, 0x80000000, v161
	v_mov_b32_e32 v133, v132
	v_mov_b32_e32 v134, v132
	v_mov_b32_e32 v135, v132
	v_cvt_pk_bf16_f32 v92, v0, v2
	v_cvt_pk_bf16_f32 v93, v3, v164
	v_cvt_pk_bf16_f32 v94, v165, v166
	v_cvt_pk_bf16_f32 v95, v167, v168
	v_cvt_pk_bf16_f32 v96, v169, v170
	v_cvt_pk_bf16_f32 v97, v171, v172
	v_cvt_pk_bf16_f32 v98, v173, v174
	v_cvt_pk_bf16_f32 v99, v175, v176
	v_cvt_pk_bf16_f32 v84, v177, v178
	v_cvt_pk_bf16_f32 v85, v179, v180
	v_cvt_pk_bf16_f32 v86, v181, v182
	v_cvt_pk_bf16_f32 v87, v183, v184
	v_cvt_pk_bf16_f32 v88, v185, v186
	v_cvt_pk_bf16_f32 v89, v187, v188
	v_cvt_pk_bf16_f32 v90, v189, v190
	v_cvt_pk_bf16_f32 v91, v191, v192
	v_add_u32_e32 v194, s65, v156
	ds_read_b128 v[100:103], v194
	v_add_u32_e32 v193, s65, v157
	ds_read_b128 v[104:107], v193
	ds_read_b128 v[108:111], v194 offset:4096
	s_waitcnt lgkmcnt(2)
	v_mfma_f32_16x16x32_bf16 v[100:103], v[100:103], v[44:47], v[132:135]
	ds_read_b128 v[112:115], v193 offset:4096
	s_waitcnt lgkmcnt(2)
	v_mfma_f32_16x16x32_bf16 v[100:103], v[104:107], v[52:55], v[100:103]
	ds_read_b128 v[104:107], v194 offset:8192
	s_waitcnt lgkmcnt(2)
	v_mfma_f32_16x16x32_bf16 v[108:111], v[108:111], v[44:47], v[132:135]
	ds_read_b128 v[116:119], v193 offset:8192
	s_waitcnt lgkmcnt(2)
	v_mfma_f32_16x16x32_bf16 v[108:111], v[112:115], v[52:55], v[108:111]
	ds_read_b128 v[120:123], v194 offset:12288
	s_waitcnt lgkmcnt(2)
	v_mfma_f32_16x16x32_bf16 v[104:107], v[104:107], v[44:47], v[132:135]
	ds_read_b128 v[124:127], v193 offset:12288
	s_waitcnt lgkmcnt(2)
	v_mfma_f32_16x16x32_bf16 v[112:115], v[116:119], v[52:55], v[104:107]
	s_waitcnt lgkmcnt(1)
	v_mfma_f32_16x16x32_bf16 v[104:107], v[120:123], v[44:47], v[132:135]
	s_waitcnt lgkmcnt(0)
	v_mfma_f32_16x16x32_bf16 v[104:107], v[124:127], v[52:55], v[104:107]
	v_cndmask_b32_e64 v117, 0, 1, s[46:47]
	v_mov_b32_e32 v116, 0xf149f2ca
	v_cmp_ne_u32_e64 s[38:39], 1, v117
	s_andn2_b64 vcc, exec, s[46:47]
	v_mov_b32_e32 v117, 0xf149f2ca
	v_mov_b32_e32 v118, 0xf149f2ca
	v_mov_b32_e32 v119, 0xf149f2ca
	v_mov_b32_e32 v120, 0xf149f2ca
	v_mov_b32_e32 v121, 0xf149f2ca
	v_mov_b32_e32 v122, 0xf149f2ca
	v_mov_b32_e32 v123, 0xf149f2ca
	v_mov_b32_e32 v124, 0xf149f2ca
	v_mov_b32_e32 v125, 0xf149f2ca
	v_mov_b32_e32 v126, 0xf149f2ca
	v_mov_b32_e32 v127, 0xf149f2ca
	v_mov_b32_e32 v128, 0xf149f2ca
	v_mov_b32_e32 v129, 0xf149f2ca
	v_mov_b32_e32 v130, 0xf149f2ca
	v_mov_b32_e32 v131, 0xf149f2ca
	s_cbranch_vccnz .LBB0_430
	ds_read_b128 v[116:119], v194 offset:32768
	ds_read_b128 v[120:123], v193 offset:32768
	ds_read_b128 v[124:127], v194 offset:36864
	s_waitcnt lgkmcnt(2)
	v_mfma_f32_16x16x32_bf16 v[116:119], v[116:119], v[44:47], v[132:135]
	ds_read_b128 v[206:209], v193 offset:36864
	s_waitcnt lgkmcnt(2)
	v_mfma_f32_16x16x32_bf16 v[128:131], v[120:123], v[52:55], v[116:119]
	s_nop 4
	ds_read_b128 v[116:119], v194 offset:40960
	s_waitcnt lgkmcnt(2)
	v_mfma_f32_16x16x32_bf16 v[120:123], v[124:127], v[44:47], v[132:135]
	ds_read_b128 v[210:213], v193 offset:40960
	s_waitcnt lgkmcnt(2)
	v_mfma_f32_16x16x32_bf16 v[124:127], v[206:209], v[52:55], v[120:123]
	ds_read_b128 v[206:209], v194 offset:45056
	s_waitcnt lgkmcnt(2)
	v_mfma_f32_16x16x32_bf16 v[116:119], v[116:119], v[44:47], v[132:135]
	ds_read_b128 v[214:217], v193 offset:45056
	s_waitcnt lgkmcnt(2)
	v_mfma_f32_16x16x32_bf16 v[120:123], v[210:213], v[52:55], v[116:119]
	s_waitcnt lgkmcnt(1)
	v_mfma_f32_16x16x32_bf16 v[116:119], v[206:209], v[44:47], v[132:135]
	s_waitcnt lgkmcnt(0)
	v_mfma_f32_16x16x32_bf16 v[116:119], v[214:217], v[52:55], v[116:119]

.LBB0_437:
	v_add_u32_e32 v216, s65, v158
	ds_read_b128 v[218:221], v216 offset:16384
	v_add_u32_e32 v215, s65, v159
	ds_read_b128 v[232:235], v215 offset:16384
	ds_read_b128 v[236:239], v216 offset:18432
	s_waitcnt lgkmcnt(2)
	v_mfma_f32_16x16x32_bf16 v[72:75], v[218:221], v[92:95], v[72:75]
	v_mfma_f32_16x16x32_bf16 v[80:83], v[218:221], v[112:115], v[80:83]
	ds_read_b128 v[218:221], v215 offset:18432
	s_waitcnt lgkmcnt(2)
	v_mfma_f32_16x16x32_bf16 v[72:75], v[232:235], v[96:99], v[72:75]
	v_mfma_f32_16x16x32_bf16 v[80:83], v[232:235], v[108:111], v[80:83]
	ds_read_b128 v[232:235], v216 offset:20480
	s_waitcnt lgkmcnt(2)
	v_mfma_f32_16x16x32_bf16 v[68:71], v[236:239], v[92:95], v[68:71]
	v_mfma_f32_16x16x32_bf16 v[76:79], v[236:239], v[112:115], v[76:79]
	ds_read_b128 v[236:239], v215 offset:20480
	s_waitcnt lgkmcnt(2)
	v_mfma_f32_16x16x32_bf16 v[68:71], v[218:221], v[96:99], v[68:71]
	v_mfma_f32_16x16x32_bf16 v[76:79], v[218:221], v[108:111], v[76:79]
	ds_read_b128 v[218:221], v216 offset:22528
	s_waitcnt lgkmcnt(2)
	v_mfma_f32_16x16x32_bf16 v[60:63], v[232:235], v[92:95], v[60:63]
	v_mfma_f32_16x16x32_bf16 v[64:67], v[232:235], v[112:115], v[64:67]
	ds_read_b128 v[232:235], v215 offset:22528
	s_waitcnt lgkmcnt(2)
	v_mfma_f32_16x16x32_bf16 v[60:63], v[236:239], v[96:99], v[60:63]
	v_mfma_f32_16x16x32_bf16 v[64:67], v[236:239], v[108:111], v[64:67]
	ds_read_b128 v[236:239], v216 offset:24576
	s_waitcnt lgkmcnt(2)
	v_mfma_f32_16x16x32_bf16 v[32:35], v[218:221], v[92:95], v[32:35]
	v_mfma_f32_16x16x32_bf16 v[56:59], v[218:221], v[112:115], v[56:59]
	ds_read_b128 v[218:221], v215 offset:24576
	s_waitcnt lgkmcnt(2)
	v_mfma_f32_16x16x32_bf16 v[32:35], v[232:235], v[96:99], v[32:35]
	v_mfma_f32_16x16x32_bf16 v[56:59], v[232:235], v[108:111], v[56:59]
	ds_read_b128 v[232:235], v216 offset:26624
	s_waitcnt lgkmcnt(2)
	v_mfma_f32_16x16x32_bf16 v[24:27], v[236:239], v[92:95], v[24:27]
	v_mfma_f32_16x16x32_bf16 v[28:31], v[236:239], v[112:115], v[28:31]
	ds_read_b128 v[236:239], v215 offset:26624
	s_waitcnt lgkmcnt(2)
	v_mfma_f32_16x16x32_bf16 v[24:27], v[218:221], v[96:99], v[24:27]
	v_mfma_f32_16x16x32_bf16 v[28:31], v[218:221], v[108:111], v[28:31]
	ds_read_b128 v[218:221], v216 offset:28672
	s_waitcnt lgkmcnt(2)
	v_mfma_f32_16x16x32_bf16 v[16:19], v[232:235], v[92:95], v[16:19]
	v_mfma_f32_16x16x32_bf16 v[20:23], v[232:235], v[112:115], v[20:23]
	ds_read_b128 v[232:235], v215 offset:28672
	s_waitcnt lgkmcnt(2)
	v_mfma_f32_16x16x32_bf16 v[16:19], v[236:239], v[96:99], v[16:19]
	v_mfma_f32_16x16x32_bf16 v[20:23], v[236:239], v[108:111], v[20:23]
	ds_read_b128 v[236:239], v216 offset:30720
	s_waitcnt lgkmcnt(2)
	v_mfma_f32_16x16x32_bf16 v[8:11], v[218:221], v[92:95], v[8:11]
	v_mfma_f32_16x16x32_bf16 v[12:15], v[218:221], v[112:115], v[12:15]
	ds_read_b128 v[218:221], v215 offset:30720
	s_waitcnt lgkmcnt(1)
	v_mfma_f32_16x16x32_bf16 v[4:7], v[236:239], v[92:95], v[4:7]
	v_mfma_f32_16x16x32_bf16 v[48:51], v[236:239], v[112:115], v[48:51]
	v_mfma_f32_16x16x32_bf16 v[8:11], v[232:235], v[96:99], v[8:11]
	v_mfma_f32_16x16x32_bf16 v[12:15], v[232:235], v[108:111], v[12:15]
	s_waitcnt lgkmcnt(0)
	v_mfma_f32_16x16x32_bf16 v[4:7], v[218:221], v[96:99], v[4:7]
	v_mfma_f32_16x16x32_bf16 v[48:51], v[218:221], v[108:111], v[48:51]
	s_and_b64 vcc, exec, s[38:39]
	s_cbranch_vccnz .LBB0_420
	ds_read_b128 v[92:95], v216 offset:49152
	ds_read_b128 v[96:99], v215 offset:49152
	ds_read_b128 v[108:111], v216 offset:51200
	s_waitcnt lgkmcnt(2)
	v_mfma_f32_16x16x32_bf16 v[72:75], v[92:95], v[84:87], v[72:75]
	v_mfma_f32_16x16x32_bf16 v[80:83], v[92:95], v[104:107], v[80:83]
	ds_read_b128 v[92:95], v215 offset:51200
	s_waitcnt lgkmcnt(2)
	v_mfma_f32_16x16x32_bf16 v[72:75], v[96:99], v[88:91], v[72:75]
	v_mfma_f32_16x16x32_bf16 v[80:83], v[96:99], v[100:103], v[80:83]
	ds_read_b128 v[96:99], v216 offset:53248
	s_waitcnt lgkmcnt(2)
	v_mfma_f32_16x16x32_bf16 v[68:71], v[108:111], v[84:87], v[68:71]
	v_mfma_f32_16x16x32_bf16 v[76:79], v[108:111], v[104:107], v[76:79]
	ds_read_b128 v[108:111], v215 offset:53248
	s_waitcnt lgkmcnt(2)
	v_mfma_f32_16x16x32_bf16 v[68:71], v[92:95], v[88:91], v[68:71]
	v_mfma_f32_16x16x32_bf16 v[76:79], v[92:95], v[100:103], v[76:79]
	ds_read_b128 v[92:95], v216 offset:55296
	s_waitcnt lgkmcnt(2)
	v_mfma_f32_16x16x32_bf16 v[60:63], v[96:99], v[84:87], v[60:63]
	v_mfma_f32_16x16x32_bf16 v[64:67], v[96:99], v[104:107], v[64:67]
	ds_read_b128 v[96:99], v215 offset:55296
	s_waitcnt lgkmcnt(2)
	v_mfma_f32_16x16x32_bf16 v[60:63], v[108:111], v[88:91], v[60:63]
	v_mfma_f32_16x16x32_bf16 v[64:67], v[108:111], v[100:103], v[64:67]
	ds_read_b128 v[108:111], v216 offset:57344
	s_waitcnt lgkmcnt(2)
	v_mfma_f32_16x16x32_bf16 v[32:35], v[92:95], v[84:87], v[32:35]
	v_mfma_f32_16x16x32_bf16 v[56:59], v[92:95], v[104:107], v[56:59]
	ds_read_b128 v[92:95], v215 offset:57344
	s_waitcnt lgkmcnt(2)
	v_mfma_f32_16x16x32_bf16 v[32:35], v[96:99], v[88:91], v[32:35]
	v_mfma_f32_16x16x32_bf16 v[56:59], v[96:99], v[100:103], v[56:59]
	ds_read_b128 v[96:99], v216 offset:59392
	s_waitcnt lgkmcnt(2)
	v_mfma_f32_16x16x32_bf16 v[24:27], v[108:111], v[84:87], v[24:27]
	v_mfma_f32_16x16x32_bf16 v[28:31], v[108:111], v[104:107], v[28:31]
	ds_read_b128 v[108:111], v215 offset:59392
	s_waitcnt lgkmcnt(2)
	v_mfma_f32_16x16x32_bf16 v[24:27], v[92:95], v[88:91], v[24:27]
	v_mfma_f32_16x16x32_bf16 v[28:31], v[92:95], v[100:103], v[28:31]
	ds_read_b128 v[92:95], v216 offset:61440
	s_waitcnt lgkmcnt(2)
	v_mfma_f32_16x16x32_bf16 v[16:19], v[96:99], v[84:87], v[16:19]
	v_mfma_f32_16x16x32_bf16 v[20:23], v[96:99], v[104:107], v[20:23]
	ds_read_b128 v[96:99], v215 offset:61440
	s_waitcnt lgkmcnt(2)
	v_mfma_f32_16x16x32_bf16 v[16:19], v[108:111], v[88:91], v[16:19]
	v_mfma_f32_16x16x32_bf16 v[20:23], v[108:111], v[100:103], v[20:23]
	ds_read_b128 v[108:111], v216 offset:63488
	s_waitcnt lgkmcnt(2)
	v_mfma_f32_16x16x32_bf16 v[8:11], v[92:95], v[84:87], v[8:11]
	v_mfma_f32_16x16x32_bf16 v[12:15], v[92:95], v[104:107], v[12:15]
	ds_read_b128 v[92:95], v215 offset:63488
	s_waitcnt lgkmcnt(1)
	v_mfma_f32_16x16x32_bf16 v[4:7], v[108:111], v[84:87], v[4:7]
	v_mfma_f32_16x16x32_bf16 v[48:51], v[108:111], v[104:107], v[48:51]
	v_mfma_f32_16x16x32_bf16 v[8:11], v[96:99], v[88:91], v[8:11]
	v_mfma_f32_16x16x32_bf16 v[12:15], v[96:99], v[100:103], v[12:15]
	s_waitcnt lgkmcnt(0)
	v_mfma_f32_16x16x32_bf16 v[4:7], v[92:95], v[88:91], v[4:7]
	v_mfma_f32_16x16x32_bf16 v[48:51], v[92:95], v[100:103], v[48:51]
	s_branch .LBB0_420
